# code placement: P5 head-loop variants shifted by 8 bytes (unreachable pad nops before and after, later code keeps its phase)
# speedup vs baseline: 1.0048x; 1.0048x over previous
; __device__ __forceinline__ f32x16 mfma32(bf16x8 a, bf16x8 b, f32x16 c) { return __builtin_amdgcn_mfma_f32_32x32x16_bf16(a, b, c, 0, 0, 0); }
; __device__ __forceinline__ void phase_ssd_y(const PT& p, LAS unsigned char* lds, int tid, int lane, int wave) {
;     ...
;         float ssq = 0.f;
; #pragma unroll 2
;         for (int r = 0; r < 8; ++r) {
;             const int hh = grp * 8 + r;
;             f32x16 acc;
; #pragma unroll
;             for (int i = 0; i < 16; ++i) acc[i] = 0.f;
;             const bf16* pp = PV + ((size_t)(bc * 32 + hh) * 64 + pb * 32 + r32) * 128 + 8 * h;
; #pragma unroll
;             for (int st = 0; st < 8; ++st) acc = mfma32(ld_frag16(pp + 16 * st), cf[st], acc);
;             const float al = acum[r * 128 + l]; const float el = __expf(al); const float dsk = p.in[11][hh];
.LBB0_495:
	v_readfirstlane_b32 s98, v117
	v_bfe_u32 v164, v117, 5, 1
	s_nop 3
	s_bfe_u32 s98, s98, 0x20006
	v_bfe_u32 v165, v117, 8, 1
	v_mov_b32_e32 v163, 0xbfb8aa3b
	v_lshlrev_b32_e32 v244, 2, v164
	v_sub_u32_e32 v160, v116, v244
	v_lshlrev_b32_e32 v161, 4, v164
	v_lshlrev_b32_e32 v141, 2, v124
	v_mul_u32_u24_e32 v162, 0x410, v124
	v_lshlrev_b32_e32 v245, 6, v165
	v_lshlrev_b32_e32 v244, 3, v164
	v_add3_u32 v162, v162, v245, v244
	v_add_u32_e32 v162, 0x2600, v162
	ds_read_b64 v[112:113], v188
	v_mov_b32_e32 v126, v210
	s_waitcnt lgkmcnt(0)
	v_readfirstlane_b32 s84, v112
	v_readfirstlane_b32 s85, v113
	s_nop 3
	s_add_u32 s84, s84, s2
	s_addc_u32 s85, s85, s3
	s_cmp_eq_u32 s98, 0
	s_cbranch_scc1 .Lp5v0
	s_cmp_eq_u32 s98, 1
	s_cbranch_scc1 .Lp5v1
	s_cmp_eq_u32 s98, 2
	s_cbranch_scc1 .Lp5v2
	s_branch .Lp5v3
	s_nop 0
	s_nop 0

; #define LAS __attribute__((address_space(3)))
; __device__ __forceinline__ f32x16 mfma32(bf16x8 a, bf16x8 b, f32x16 c) { return __builtin_amdgcn_mfma_f32_32x32x16_bf16(a, b, c, 0, 0, 0); }
; __device__ __forceinline__ void phase_ssd_y(const PT& p, LAS unsigned char* lds, int tid, int lane, int wave) {
;     ...
;         for (int r = 0; r < 8; ++r) {
;             const int hh = grp * 8 + r;
;             f32x16 acc;
; #pragma unroll
;             for (int i = 0; i < 16; ++i) acc[i] = 0.f;
;             const bf16* pp = PV + ((size_t)(bc * 32 + hh) * 64 + pb * 32 + r32) * 128 + 8 * h;
; #pragma unroll
;             for (int st = 0; st < 8; ++st) acc = mfma32(ld_frag16(pp + 16 * st), cf[st], acc);
;             const float al = acum[r * 128 + l]; const float el = __expf(al); const float dsk = p.in[11][hh];
; #pragma unroll
;             for (int i = 0; i < 16; ++i) acc[i] *= el;
;             const bf16* xrow = xT + ((size_t)bc * 2048 + hh * 64 + pb * 32 + r32) * 128 + 4 * h;
; #pragma unroll
;             for (int sb = 0; sb < 4; ++sb) {
;                 if (sb <= lb) {
;                     f32x16 mm;
; #pragma unroll
;                     for (int qd = 0; qd < 4; ++qd) {
;                         const int s0 = sb * 32 + 8 * qd + 4 * h;
;                         const f32x4 as = *(const LAS f32x4*)(acum + r * 128 + s0), ds = *(const LAS f32x4*)(dtt + r * 128 + s0);
; #pragma unroll
;                         for (int j = 0; j < 4; ++j) { const float v = X[sb][4 * qd + j] * __expf(al - as[j]) * ds[j]; mm[4 * qd + j] = (s0 + j < l) ? v : ((s0 + j == l) ? v + dsk : 0.f); }
;                     }
; #pragma unroll
;                     for (int s2 = 0; s2 < 2; ++s2) acc = mfma32(ld_frag8x2(xrow + sb * 32 + 16 * s2), pack_frag(mm, s2), acc);
.Lp5v0_head:
	s_add_u32 s100, s94, 0x4000
	s_mov_b32 s101, 0
	ds_read_b32 v158, v141
	v_lshl_add_u64 v[212:213], v[142:143], 0, s[100:101]
	s_waitcnt vmcnt(10)
	v_mfma_f32_32x32x16_bf16 v[64:79], v[170:173], v[80:83], 0
	global_load_dwordx4 v[170:173], v[212:213], off
	s_waitcnt vmcnt(10)
	v_mfma_f32_32x32x16_bf16 v[64:79], v[174:177], v[84:87], v[64:79]
	global_load_dwordx4 v[174:177], v[212:213], off offset:32
	s_waitcnt vmcnt(10)
	v_mfma_f32_32x32x16_bf16 v[64:79], v[178:181], v[88:91], v[64:79]
	global_load_dwordx4 v[178:181], v[212:213], off offset:64
	s_waitcnt vmcnt(10)
	v_mfma_f32_32x32x16_bf16 v[64:79], v[220:223], v[92:95], v[64:79]
	global_load_dwordx4 v[220:223], v[212:213], off offset:96
	s_waitcnt vmcnt(10)
	v_mfma_f32_32x32x16_bf16 v[64:79], v[224:227], v[96:99], v[64:79]
	global_load_dwordx4 v[224:227], v[212:213], off offset:128
	s_waitcnt vmcnt(10)
	v_mfma_f32_32x32x16_bf16 v[64:79], v[228:231], v[100:103], v[64:79]
	global_load_dwordx4 v[228:231], v[212:213], off offset:160
	s_waitcnt vmcnt(10)
	v_mfma_f32_32x32x16_bf16 v[64:79], v[232:235], v[104:107], v[64:79]
	global_load_dwordx4 v[232:235], v[212:213], off offset:192
	s_waitcnt vmcnt(10)
	v_mfma_f32_32x32x16_bf16 v[64:79], v[208:211], v[108:111], v[64:79]
	global_load_dwordx4 v[208:211], v[212:213], off offset:224
	s_waitcnt lgkmcnt(0)
	v_mul_f32_e32 v164, 0x3fb8aa3b, v158
	v_exp_f32_e32 v165, v164
	v_mov_b32_e32 v158, v164
	s_nop 8
	v_mul_f32_e32 v64, v165, v64
	v_mul_f32_e32 v65, v165, v65
	v_mul_f32_e32 v66, v165, v66
	v_mul_f32_e32 v67, v165, v67
	v_mul_f32_e32 v68, v165, v68
	v_mul_f32_e32 v69, v165, v69
	v_mul_f32_e32 v70, v165, v70
	v_mul_f32_e32 v71, v165, v71
	v_mul_f32_e32 v72, v165, v72
	v_mul_f32_e32 v73, v165, v73
	v_mul_f32_e32 v74, v165, v74
	v_mul_f32_e32 v75, v165, v75
	v_mul_f32_e32 v76, v165, v76
	v_mul_f32_e32 v77, v165, v77
	v_mul_f32_e32 v78, v165, v78
	v_mul_f32_e32 v79, v165, v79
	ds_read_b128 v[236:239], v161 offset:4096
	ds_read_b128 v[250:253], v161 offset:4128
	s_waitcnt lgkmcnt(1)
	v_add_f32_e32 v164, v158, v236
	v_add_f32_e32 v165, v158, v237
	v_add_f32_e32 v244, v158, v238
	v_add_f32_e32 v245, v158, v239
	v_exp_f32_e32 v164, v164
	v_exp_f32_e32 v165, v165
	v_exp_f32_e32 v244, v244
	v_exp_f32_e32 v245, v245
	ds_read_b128 v[236:239], v161 offset:4160
	v_mul_f32_e32 v212, v0, v164
	v_mul_f32_e32 v213, v1, v165
	v_mul_f32_e32 v214, v2, v244
	v_mul_f32_e32 v215, v3, v245
	s_waitcnt lgkmcnt(1)
	v_add_f32_e32 v164, v158, v250
	v_add_f32_e32 v165, v158, v251
	v_add_f32_e32 v244, v158, v252
	v_add_f32_e32 v245, v158, v253
	v_exp_f32_e32 v164, v164
	v_exp_f32_e32 v165, v165
	v_exp_f32_e32 v244, v244
	v_exp_f32_e32 v245, v245
	ds_read_b128 v[250:253], v161 offset:4192
	v_mul_f32_e32 v216, v4, v164
	v_mul_f32_e32 v217, v5, v165
	v_mul_f32_e32 v218, v6, v244
	v_mul_f32_e32 v219, v7, v245
	s_waitcnt vmcnt(10)
	v_add_f32_e32 v169, v212, v159
	v_add_f32_e32 v183, v213, v159
	v_cmp_eq_u32_e32 vcc, 0, v160
	v_cmp_eq_u32_e64 s[100:101], 1, v160
	s_nop 0
	v_cndmask_b32_e32 v169, 0, v169, vcc
	v_cndmask_b32_e64 v183, 0, v183, s[100:101]
	v_cmp_lt_i32_e32 vcc, 0, v160
	v_cmp_lt_i32_e64 s[100:101], 1, v160
	s_nop 0
	v_cndmask_b32_e32 v212, v169, v212, vcc
	v_cndmask_b32_e64 v213, v183, v213, s[100:101]
	v_add_f32_e32 v169, v214, v159
	v_add_f32_e32 v183, v215, v159
	v_cmp_eq_u32_e32 vcc, 2, v160
	v_cmp_eq_u32_e64 s[100:101], 3, v160
	s_nop 0
	v_cndmask_b32_e32 v169, 0, v169, vcc
	v_cndmask_b32_e64 v183, 0, v183, s[100:101]
	v_cmp_lt_i32_e32 vcc, 2, v160
	v_cmp_lt_i32_e64 s[100:101], 3, v160
	s_nop 0
	v_cndmask_b32_e32 v214, v169, v214, vcc
	v_cndmask_b32_e64 v215, v183, v215, s[100:101]
	v_add_f32_e32 v169, v216, v159
	v_add_f32_e32 v183, v217, v159
	v_cmp_eq_u32_e32 vcc, 8, v160
	v_cmp_eq_u32_e64 s[100:101], 9, v160
	s_nop 0
	v_cndmask_b32_e32 v169, 0, v169, vcc
	v_cndmask_b32_e64 v183, 0, v183, s[100:101]
	v_cmp_lt_i32_e32 vcc, 8, v160
	v_cmp_lt_i32_e64 s[100:101], 9, v160
	s_nop 0
	v_cndmask_b32_e32 v216, v169, v216, vcc
	v_cndmask_b32_e64 v217, v183, v217, s[100:101]
	v_add_f32_e32 v169, v218, v159
	v_add_f32_e32 v183, v219, v159
	v_cmp_eq_u32_e32 vcc, 10, v160
	v_cmp_eq_u32_e64 s[100:101], 11, v160
	s_nop 0
	v_cndmask_b32_e32 v169, 0, v169, vcc
	v_cndmask_b32_e64 v183, 0, v183, s[100:101]
	v_cmp_lt_i32_e32 vcc, 10, v160
	v_cmp_lt_i32_e64 s[100:101], 11, v160
	s_nop 0
	v_cndmask_b32_e32 v218, v169, v218, vcc
	v_cndmask_b32_e64 v219, v183, v219, s[100:101]
	v_cvt_pk_bf16_f32 v212, v212, v213
	v_cvt_pk_bf16_f32 v213, v214, v215
	v_cvt_pk_bf16_f32 v214, v216, v217
	v_cvt_pk_bf16_f32 v215, v218, v219
	s_nop 0
	s_waitcnt vmcnt(8)
	v_permlane32_swap_b32_e32 v150, v152
	v_permlane32_swap_b32_e32 v151, v153
	v_permlane32_swap_b32_e32 v154, v156
	v_permlane32_swap_b32_e32 v155, v157
	s_nop 1
	v_mfma_f32_32x32x16_bf16 v[64:79], v[150:153], v[212:215], v[64:79]
	s_waitcnt lgkmcnt(1)
	v_add_f32_e32 v164, v158, v236
	v_add_f32_e32 v165, v158, v237
	v_add_f32_e32 v244, v158, v238
	v_add_f32_e32 v245, v158, v239
	v_exp_f32_e32 v164, v164
	v_exp_f32_e32 v165, v165
	v_exp_f32_e32 v244, v244
	v_exp_f32_e32 v245, v245
	v_mul_f32_e32 v212, v8, v164
	v_mul_f32_e32 v213, v9, v165
	v_mul_f32_e32 v214, v10, v244
	v_mul_f32_e32 v215, v11, v245
	s_waitcnt lgkmcnt(0)
; #define LAS __attribute__((address_space(3)))
; __device__ __forceinline__ float bflo(unsigned u) { return __uint_as_float(u << 16); }
; __device__ __forceinline__ float bfhi(unsigned u) { return __uint_as_float(u & 0xffff0000u); }
; __device__ __forceinline__ f32x16 mfma32(bf16x8 a, bf16x8 b, f32x16 c) { return __builtin_amdgcn_mfma_f32_32x32x16_bf16(a, b, c, 0, 0, 0); }
; __device__ __forceinline__ void phase_ssd_y(const PT& p, LAS unsigned char* lds, int tid, int lane, int wave) {
;     ...
;                     for (int qd = 0; qd < 4; ++qd) {
;                         const int s0 = sb * 32 + 8 * qd + 4 * h;
;                         const f32x4 as = *(const LAS f32x4*)(acum + r * 128 + s0), ds = *(const LAS f32x4*)(dtt + r * 128 + s0);
; #pragma unroll
;                         for (int j = 0; j < 4; ++j) { const float v = X[sb][4 * qd + j] * __expf(al - as[j]) * ds[j]; mm[4 * qd + j] = (s0 + j < l) ? v : ((s0 + j == l) ? v + dsk : 0.f); }
;                     }
; #pragma unroll
;                     for (int s2 = 0; s2 < 2; ++s2) acc = mfma32(ld_frag8x2(xrow + sb * 32 + 16 * s2), pack_frag(mm, s2), acc);
;                 }
;             }
; #pragma unroll
;             for (int qd = 0; qd < 4; ++qd) {
;                 LAS u32x2* yp = (LAS u32x2*)(tile + l * SY_TP + (r * 64 + pb * 32 + 8 * qd + 4 * h) * 2); const u32x2 zz = *yp;
;                 const float y0 = acc[4 * qd] * bflo(zz.x), y1 = acc[4 * qd + 1] * bfhi(zz.x);
;                 const float y2 = acc[4 * qd + 2] * bflo(zz.y), y3 = acc[4 * qd + 3] * bfhi(zz.y);
;                 ssq += (y0 * y0 + y1 * y1) + (y2 * y2 + y3 * y3);
;                 u32x2 w; w.x = pk2(y0, y1); w.y = pk2(y2, y3); *yp = w;
;             }
	v_add_f32_e32 v164, v158, v250
	v_add_f32_e32 v165, v158, v251
	v_add_f32_e32 v244, v158, v252
	v_add_f32_e32 v245, v158, v253
	v_exp_f32_e32 v164, v164
	v_exp_f32_e32 v165, v165
	v_exp_f32_e32 v244, v244
	v_exp_f32_e32 v245, v245
	v_mul_f32_e32 v216, v12, v164
	v_mul_f32_e32 v217, v13, v165
	v_mul_f32_e32 v218, v14, v244
	v_mul_f32_e32 v219, v15, v245
	v_add_f32_e32 v169, v212, v159
	v_add_f32_e32 v183, v213, v159
	v_cmp_eq_u32_e32 vcc, 16, v160
	v_cmp_eq_u32_e64 s[100:101], 17, v160
	s_nop 0
	v_cndmask_b32_e32 v169, 0, v169, vcc
	v_cndmask_b32_e64 v183, 0, v183, s[100:101]
	v_cmp_lt_i32_e32 vcc, 16, v160
	v_cmp_lt_i32_e64 s[100:101], 17, v160
	s_nop 0
	v_cndmask_b32_e32 v212, v169, v212, vcc
	v_cndmask_b32_e64 v213, v183, v213, s[100:101]
	v_add_f32_e32 v169, v214, v159
	v_add_f32_e32 v183, v215, v159
	v_cmp_eq_u32_e32 vcc, 18, v160
	v_cmp_eq_u32_e64 s[100:101], 19, v160
	s_nop 0
	v_cndmask_b32_e32 v169, 0, v169, vcc
	v_cndmask_b32_e64 v183, 0, v183, s[100:101]
	v_cmp_lt_i32_e32 vcc, 18, v160
	v_cmp_lt_i32_e64 s[100:101], 19, v160
	s_nop 0
	v_cndmask_b32_e32 v214, v169, v214, vcc
	v_cndmask_b32_e64 v215, v183, v215, s[100:101]
	v_add_f32_e32 v169, v216, v159
	v_add_f32_e32 v183, v217, v159
	v_cmp_eq_u32_e32 vcc, 24, v160
	v_cmp_eq_u32_e64 s[100:101], 25, v160
	s_nop 0
	v_cndmask_b32_e32 v169, 0, v169, vcc
	v_cndmask_b32_e64 v183, 0, v183, s[100:101]
	v_cmp_lt_i32_e32 vcc, 24, v160
	v_cmp_lt_i32_e64 s[100:101], 25, v160
	s_nop 0
	v_cndmask_b32_e32 v216, v169, v216, vcc
	v_cndmask_b32_e64 v217, v183, v217, s[100:101]
	v_add_f32_e32 v169, v218, v159
	v_add_f32_e32 v183, v219, v159
	v_cmp_eq_u32_e32 vcc, 26, v160
	v_cmp_eq_u32_e64 s[100:101], 27, v160
	s_nop 0
	v_cndmask_b32_e32 v169, 0, v169, vcc
	v_cndmask_b32_e64 v183, 0, v183, s[100:101]
	v_cmp_lt_i32_e32 vcc, 26, v160
	v_cmp_lt_i32_e64 s[100:101], 27, v160
	s_nop 0
	v_cndmask_b32_e32 v218, v169, v218, vcc
	v_cndmask_b32_e64 v219, v183, v219, s[100:101]
	s_cmp_eq_u32 s94, 0x1c000
	s_cselect_b32 s100, 0, 4
	s_add_u32 s84, s84, s100
	s_addc_u32 s85, s85, 0
	v_mov_b32_e32 v164, 0
	global_load_dword v159, v164, s[84:85]
	v_cvt_pk_bf16_f32 v212, v212, v213
	v_cvt_pk_bf16_f32 v213, v214, v215
	v_cvt_pk_bf16_f32 v214, v216, v217
	v_cvt_pk_bf16_f32 v215, v218, v219
	s_nop 0
	s_nop 0
	v_mfma_f32_32x32x16_bf16 v[64:79], v[154:157], v[212:215], v[64:79]
	global_load_dwordx4 v[150:153], v[184:185], off offset:0
	global_load_dwordx4 v[154:157], v[184:185], off offset:32
	s_nop 10
	ds_read_b64 v[216:217], v162 offset:0
	s_waitcnt lgkmcnt(0)
	v_lshlrev_b32_e32 v169, 16, v216
	v_and_b32_e32 v183, 0xffff0000, v216
	v_lshlrev_b32_e32 v254, 16, v217
	v_and_b32_e32 v255, 0xffff0000, v217
	v_mul_f32_e32 v169, v64, v169
	v_mul_f32_e32 v183, v65, v183
	v_mul_f32_e32 v254, v66, v254
	v_mul_f32_e32 v255, v67, v255
	v_mul_f32_e32 v164, v169, v169
	v_mul_f32_e32 v165, v254, v254
	v_fmac_f32_e32 v164, v183, v183
	v_fmac_f32_e32 v165, v255, v255
	v_cvt_pk_bf16_f32 v216, v169, v183
	v_cvt_pk_bf16_f32 v217, v254, v255
	v_add_f32_e32 v164, v164, v165
	ds_write_b64 v162, v[216:217] offset:0
	v_add_f32_e32 v126, v126, v164
	ds_read_b64 v[216:217], v162 offset:16
	s_waitcnt lgkmcnt(0)
	v_lshlrev_b32_e32 v169, 16, v216
	v_and_b32_e32 v183, 0xffff0000, v216
	v_lshlrev_b32_e32 v254, 16, v217
	v_and_b32_e32 v255, 0xffff0000, v217
	v_mul_f32_e32 v169, v68, v169
	v_mul_f32_e32 v183, v69, v183
	v_mul_f32_e32 v254, v70, v254
	v_mul_f32_e32 v255, v71, v255
	v_mul_f32_e32 v164, v169, v169
	v_mul_f32_e32 v165, v254, v254
	v_fmac_f32_e32 v164, v183, v183
	v_fmac_f32_e32 v165, v255, v255
	v_cvt_pk_bf16_f32 v216, v169, v183
	v_cvt_pk_bf16_f32 v217, v254, v255
	v_add_f32_e32 v164, v164, v165
	ds_write_b64 v162, v[216:217] offset:16
	v_add_f32_e32 v126, v126, v164
	ds_read_b64 v[216:217], v162 offset:32
	s_waitcnt lgkmcnt(0)
	v_lshlrev_b32_e32 v169, 16, v216
	v_and_b32_e32 v183, 0xffff0000, v216
	v_lshlrev_b32_e32 v254, 16, v217
	v_and_b32_e32 v255, 0xffff0000, v217
	v_mul_f32_e32 v169, v72, v169
	v_mul_f32_e32 v183, v73, v183
	v_mul_f32_e32 v254, v74, v254
	v_mul_f32_e32 v255, v75, v255
	v_mul_f32_e32 v164, v169, v169
	v_mul_f32_e32 v165, v254, v254
	v_fmac_f32_e32 v164, v183, v183
	v_fmac_f32_e32 v165, v255, v255
	v_cvt_pk_bf16_f32 v216, v169, v183
	v_cvt_pk_bf16_f32 v217, v254, v255
	v_add_f32_e32 v164, v164, v165
	ds_write_b64 v162, v[216:217] offset:32
	v_add_f32_e32 v126, v126, v164
	ds_read_b64 v[216:217], v162 offset:48
	s_waitcnt lgkmcnt(0)
	v_lshlrev_b32_e32 v169, 16, v216
	v_and_b32_e32 v183, 0xffff0000, v216
	v_lshlrev_b32_e32 v254, 16, v217
	v_and_b32_e32 v255, 0xffff0000, v217
	v_mul_f32_e32 v169, v76, v169
	v_mul_f32_e32 v183, v77, v183
	v_mul_f32_e32 v254, v78, v254
	v_mul_f32_e32 v255, v79, v255
	v_mul_f32_e32 v164, v169, v169
	v_mul_f32_e32 v165, v254, v254
	v_fmac_f32_e32 v164, v183, v183
	v_fmac_f32_e32 v165, v255, v255
	v_cvt_pk_bf16_f32 v216, v169, v183
	v_cvt_pk_bf16_f32 v217, v254, v255
	v_add_f32_e32 v164, v164, v165
	ds_write_b64 v162, v[216:217] offset:48
	v_add_f32_e32 v126, v126, v164
	v_add_u32_e32 v161, 0x200, v161
	v_add_u32_e32 v141, 0x200, v141
	v_add_u32_e32 v162, 0x80, v162
	v_mov_b32_e32 v206, v184
	v_mov_b32_e32 v207, v185
	v_add_co_u32_e32 v184, vcc, 0x4000, v184
	s_nop 1
	v_addc_co_u32_e32 v185, vcc, 0, v185, vcc
	s_add_u32 s94, s94, 0x4000
	s_cmp_eq_u32 s94, 0x20000
	s_cbranch_scc0 .Lp5v0_head
	s_branch .Lp5v_exit
	s_nop 0
	s_nop 0
	s_nop 0
	s_nop 0
	s_nop 0
	s_nop 0
	s_nop 0
	s_nop 0
	s_nop 0
	s_nop 0
	s_nop 0
	s_nop 0
	s_nop 0
	s_nop 0
